# P0: filter epilogue 16-byte row stores, static balance of long and short setup items over workgroups
# speedup vs baseline: 1.2443x; 1.0080x over previous
.LBB0_388:
	s_or_b64 exec, exec, s[0:1]
	v_readlane_b32 s0, v255, 17
	v_readlane_b32 s1, v255, 18
	s_andn2_b64 vcc, exec, s[0:1]
	s_cbranch_vccnz .LBB0_21
	v_readlane_b32 s25, v252, 0
	s_mov_b32 s98, 0
	v_readlane_b32 s99, v255, 35
	s_nop 0
	s_cmpk_eq_u32 s99, 0x200
	s_cbranch_scc1 .Lp0_map
	s_branch .LBB0_392

.LBB0_391:
	v_readlane_b32 s36, v255, 33
	v_readlane_b32 s38, v255, 35
	v_readlane_b32 s37, v255, 34
	v_readlane_b32 s39, v255, 36
	s_cmpk_eq_u32 s38, 0x200
	s_cbranch_scc1 .Lp0_lat
	s_add_i32 s25, s25, s38
	s_cmpk_gt_i32 s25, 0x1100
	s_cbranch_scc1 .LBB0_21
	s_branch .LBB0_392
.Lp0_next:
.Lp0_lat:
	s_add_i32 s98, s98, 1
.Lp0_map:
	v_readlane_b32 s99, v252, 0
	s_cmp_lt_u32 s98, 2
	s_cbranch_scc0 .Lp0_m2
	s_lshl_b32 s25, s98, 9
	s_add_i32 s25, s25, s99
	s_branch .Lp0_big
.Lp0_m2:
	s_cmpk_lt_u32 s99, 0x140
	s_cbranch_scc0 .Lp0_c2
	s_cmp_eq_u32 s98, 2
	s_cbranch_scc0 .Lp0_c3t
	s_add_i32 s25, s99, 0x400
	s_branch .Lp0_big
.Lp0_c3t:
	s_cmp_lt_u32 s98, 6
	s_cbranch_scc0 .LBB0_21
	s_mul_i32 s25, s99, 3
	s_add_i32 s25, s25, s98
	s_addk_i32 s25, 0x53e
	s_branch .LBB0_392
.Lp0_c2:
	s_cmp_lt_u32 s98, 13
	s_cbranch_scc0 .LBB0_21
	s_add_i32 s25, s98, -2
	s_mulk_i32 s25, 0xc0
	s_add_i32 s25, s25, s99
	s_addk_i32 s25, 0x280
	s_cmpk_lt_u32 s25, 0xbc0
	s_cbranch_scc0 .Lp0_misc
	s_addk_i32 s25, 0x541
	s_branch .LBB0_392
.Lp0_misc:
	s_cmpk_eq_u32 s25, 0xbff
	s_cbranch_scc0 .Lp0_next
	s_movk_i32 s25, 0xc0
	s_branch .LBB0_392
.Lp0_big:
	s_cmpk_lt_u32 s25, 0xc0
	s_cbranch_scc1 .LBB0_392
	s_add_i32 s25, s25, 1

.LBB0_482:
	global_load_dword v14, v[12:13], off
	v_add_u32_e32 v17, s37, v1
	v_add_u32_e32 v16, 0x400, v17
	v_add_u32_e32 v90, 0x800, v17
	v_add_u32_e32 v92, 0xc00, v17
	v_add_u32_e32 v94, 0x1000, v17
	v_add_u32_e32 v96, 0x1400, v17
	v_add_u32_e32 v98, 0x1800, v17
	v_add_u32_e32 v100, 0x1c00, v17
	v_ashrrev_i32_e32 v17, 31, v16
	v_ashrrev_i32_e32 v91, 31, v90
	v_ashrrev_i32_e32 v93, 31, v92
	v_ashrrev_i32_e32 v95, 31, v94
	v_ashrrev_i32_e32 v97, 31, v96
	v_ashrrev_i32_e32 v99, 31, v98
	v_ashrrev_i32_e32 v101, 31, v100
	v_mov_b32_e32 v15, s36
	v_lshl_add_u64 v[16:17], v[16:17], 2, s[26:27]
	v_lshl_add_u64 v[90:91], v[90:91], 2, s[26:27]
	v_lshl_add_u64 v[92:93], v[92:93], 2, s[26:27]
	v_lshl_add_u64 v[94:95], v[94:95], 2, s[26:27]
	v_lshl_add_u64 v[96:97], v[96:97], 2, s[26:27]
	v_lshl_add_u64 v[98:99], v[98:99], 2, s[26:27]
	v_lshl_add_u64 v[100:101], v[100:101], 2, s[26:27]
	ds_read_b128 v[26:29], v15
	ds_read_b128 v[30:33], v15 offset:16
	ds_read_b128 v[34:37], v15 offset:256
	ds_read_b128 v[38:41], v15 offset:272
	ds_read_b128 v[42:45], v15 offset:512
	ds_read_b128 v[46:49], v15 offset:528
	ds_read_b128 v[50:53], v15 offset:768
	ds_read_b128 v[54:57], v15 offset:784
	ds_read_b128 v[58:61], v15 offset:1024
	ds_read_b128 v[62:65], v15 offset:1040
	ds_read_b128 v[66:69], v15 offset:1280
	ds_read_b128 v[70:73], v15 offset:1296
	ds_read_b128 v[74:77], v15 offset:1536
	ds_read_b128 v[78:81], v15 offset:1552
	ds_read_b128 v[82:85], v15 offset:1792
	ds_read_b128 v[86:89], v15 offset:1808
	global_load_dword v16, v[16:17], off
	s_nop 0
	global_load_dword v90, v[90:91], off
	s_nop 0
	global_load_dword v92, v[92:93], off
	s_nop 0
	global_load_dword v94, v[94:95], off
	s_nop 0
	global_load_dword v96, v[96:97], off
	s_nop 0
	global_load_dword v98, v[98:99], off
	s_nop 0
	global_load_dword v100, v[100:101], off
	s_waitcnt lgkmcnt(13)
	v_mov_b32_e32 v103, v34
	v_mov_b32_e32 v102, v26
	s_waitcnt lgkmcnt(11)
	v_mov_b32_e32 v104, v42
	s_waitcnt lgkmcnt(9)
	v_mov_b32_e32 v105, v50
	s_waitcnt lgkmcnt(7)
	v_mov_b32_e32 v106, v58
	s_waitcnt lgkmcnt(5)
	v_mov_b32_e32 v107, v66
	s_waitcnt lgkmcnt(3)
	v_mov_b32_e32 v108, v74
	s_waitcnt lgkmcnt(1)
	v_mov_b32_e32 v109, v82
	v_mov_b32_e32 v34, v27
	v_mov_b32_e32 v50, v43
	v_mov_b32_e32 v66, v59
	v_mov_b32_e32 v82, v75
	v_mov_b32_e32 v26, v28
	v_mov_b32_e32 v27, v36
	v_mov_b32_e32 v42, v44
	v_mov_b32_e32 v43, v52
	v_mov_b32_e32 v58, v60
	v_mov_b32_e32 v59, v68
	v_mov_b32_e32 v74, v76
	v_mov_b32_e32 v75, v84
	v_mov_b32_e32 v36, v29
	v_mov_b32_e32 v52, v45
	v_mov_b32_e32 v68, v61
	v_mov_b32_e32 v84, v77
	v_mov_b32_e32 v28, v30
	v_mov_b32_e32 v29, v38
	v_mov_b32_e32 v44, v46
	v_mov_b32_e32 v45, v54
	v_mov_b32_e32 v60, v62
	v_mov_b32_e32 v61, v70
	v_mov_b32_e32 v76, v78
	s_waitcnt lgkmcnt(0)
	v_mov_b32_e32 v77, v86
	v_mov_b32_e32 v38, v31
	v_mov_b32_e32 v54, v47
	v_mov_b32_e32 v70, v63
	v_mov_b32_e32 v86, v79
	v_mov_b32_e32 v30, v32
	v_mov_b32_e32 v31, v40
	v_mov_b32_e32 v46, v48
	v_mov_b32_e32 v47, v56
	v_mov_b32_e32 v62, v64
	v_mov_b32_e32 v63, v72
	v_mov_b32_e32 v78, v80
	v_mov_b32_e32 v79, v88
	s_add_i32 s36, s36, 32
	s_addk_i32 s37, 0x2000
	v_mov_b32_e32 v40, v33
	v_mov_b32_e32 v56, v49
	v_mov_b32_e32 v72, v65
	v_mov_b32_e32 v88, v81
	v_lshl_add_u64 v[12:13], v[12:13], 0, s[34:35]
	s_cmp_eq_u32 s37, 0x10000
	s_waitcnt vmcnt(7)
	v_pk_fma_f32 v[10:11], v[14:15], v[102:103], v[10:11] op_sel_hi:[0,1,1]
	v_pk_fma_f32 v[8:9], v[14:15], v[104:105], v[8:9] op_sel_hi:[0,1,1]
	v_pk_fma_f32 v[6:7], v[14:15], v[106:107], v[6:7] op_sel_hi:[0,1,1]
	v_pk_fma_f32 v[4:5], v[14:15], v[108:109], v[4:5] op_sel_hi:[0,1,1]
	s_waitcnt vmcnt(6)
	v_pk_fma_f32 v[10:11], v[16:17], v[34:35], v[10:11] op_sel_hi:[0,1,1]
	v_pk_fma_f32 v[8:9], v[16:17], v[50:51], v[8:9] op_sel_hi:[0,1,1]
	v_pk_fma_f32 v[6:7], v[16:17], v[66:67], v[6:7] op_sel_hi:[0,1,1]
	v_pk_fma_f32 v[4:5], v[16:17], v[82:83], v[4:5] op_sel_hi:[0,1,1]
	s_waitcnt vmcnt(5)
	v_pk_fma_f32 v[10:11], v[90:91], v[26:27], v[10:11] op_sel_hi:[0,1,1]
	v_pk_fma_f32 v[8:9], v[90:91], v[42:43], v[8:9] op_sel_hi:[0,1,1]
	v_pk_fma_f32 v[6:7], v[90:91], v[58:59], v[6:7] op_sel_hi:[0,1,1]
	v_pk_fma_f32 v[4:5], v[90:91], v[74:75], v[4:5] op_sel_hi:[0,1,1]
	s_waitcnt vmcnt(4)
	v_pk_fma_f32 v[10:11], v[92:93], v[36:37], v[10:11] op_sel_hi:[0,1,1]
	v_pk_fma_f32 v[8:9], v[92:93], v[52:53], v[8:9] op_sel_hi:[0,1,1]
	v_pk_fma_f32 v[6:7], v[92:93], v[68:69], v[6:7] op_sel_hi:[0,1,1]
	v_pk_fma_f32 v[4:5], v[92:93], v[84:85], v[4:5] op_sel_hi:[0,1,1]
	s_waitcnt vmcnt(3)
	v_pk_fma_f32 v[10:11], v[94:95], v[28:29], v[10:11] op_sel_hi:[0,1,1]
	v_pk_fma_f32 v[8:9], v[94:95], v[44:45], v[8:9] op_sel_hi:[0,1,1]
	v_pk_fma_f32 v[6:7], v[94:95], v[60:61], v[6:7] op_sel_hi:[0,1,1]
	v_pk_fma_f32 v[4:5], v[94:95], v[76:77], v[4:5] op_sel_hi:[0,1,1]
	s_waitcnt vmcnt(2)
	v_pk_fma_f32 v[10:11], v[96:97], v[38:39], v[10:11] op_sel_hi:[0,1,1]
	v_pk_fma_f32 v[8:9], v[96:97], v[54:55], v[8:9] op_sel_hi:[0,1,1]
	v_pk_fma_f32 v[6:7], v[96:97], v[70:71], v[6:7] op_sel_hi:[0,1,1]
	v_pk_fma_f32 v[4:5], v[96:97], v[86:87], v[4:5] op_sel_hi:[0,1,1]
	s_waitcnt vmcnt(1)
	v_pk_fma_f32 v[10:11], v[98:99], v[30:31], v[10:11] op_sel_hi:[0,1,1]
	v_pk_fma_f32 v[8:9], v[98:99], v[46:47], v[8:9] op_sel_hi:[0,1,1]
	v_pk_fma_f32 v[6:7], v[98:99], v[62:63], v[6:7] op_sel_hi:[0,1,1]
	v_pk_fma_f32 v[4:5], v[98:99], v[78:79], v[4:5] op_sel_hi:[0,1,1]
	s_waitcnt vmcnt(0)
	v_pk_fma_f32 v[10:11], v[100:101], v[40:41], v[10:11] op_sel_hi:[0,1,1]
	v_pk_fma_f32 v[8:9], v[100:101], v[56:57], v[8:9] op_sel_hi:[0,1,1]
	v_pk_fma_f32 v[6:7], v[100:101], v[72:73], v[6:7] op_sel_hi:[0,1,1]
	v_pk_fma_f32 v[4:5], v[100:101], v[88:89], v[4:5] op_sel_hi:[0,1,1]
	s_cbranch_scc0 .LBB0_482
	s_and_b64 vcc, exec, s[28:29]
	s_cbranch_vccnz .Lf3_slow
	v_lshl_add_u32 v12, s52, 8, v0
	v_and_b32_e32 v12, 0x1ff, v12
	v_cvt_f32_u32_e32 v13, v12
	s_nop 0
	v_fmamk_f32 v26, v13, 0x3cc4df2d, v250
	v_mul_f32_e32 v32, v18, v26
	v_mul_f32_e32 v33, v19, v26
	v_mul_f32_e32 v34, v20, v26
	v_mul_f32_e32 v35, v21, v26
	v_mul_f32_e32 v36, v22, v26
	v_mul_f32_e32 v37, v23, v26
	v_mul_f32_e32 v38, v24, v26
	v_mul_f32_e32 v39, v25, v26
	v_mul_f32_e32 v32, 0x3fb8aa3b, v32
	v_mul_f32_e32 v33, 0x3fb8aa3b, v33
	v_mul_f32_e32 v34, 0x3fb8aa3b, v34
	v_mul_f32_e32 v35, 0x3fb8aa3b, v35
	v_mul_f32_e32 v36, 0x3fb8aa3b, v36
	v_mul_f32_e32 v37, 0x3fb8aa3b, v37
	v_mul_f32_e32 v38, 0x3fb8aa3b, v38
	v_mul_f32_e32 v39, 0x3fb8aa3b, v39
	v_exp_f32_e32 v32, v32
	v_exp_f32_e32 v33, v33
	v_exp_f32_e32 v34, v34
	v_exp_f32_e32 v35, v35
	v_exp_f32_e32 v36, v36
	v_exp_f32_e32 v37, v37
	v_exp_f32_e32 v38, v38
	v_exp_f32_e32 v39, v39
	v_mul_u32_u24_e32 v12, s54, v12
	v_lshlrev_b32_e32 v130, 1, v12
	v_mul_f32_e32 v10, v32, v10
	v_mul_f32_e32 v11, v33, v11
	v_mul_f32_e32 v8, v34, v8
	v_mul_f32_e32 v9, v35, v9
	v_mul_f32_e32 v6, v36, v6
	v_mul_f32_e32 v7, v37, v7
	v_mul_f32_e32 v4, v38, v4
	v_mul_f32_e32 v5, v39, v5
	v_bfe_u32 v32, v10, 16, 1
	v_bfe_u32 v33, v11, 16, 1
	v_bfe_u32 v34, v8, 16, 1
	v_bfe_u32 v35, v9, 16, 1
	v_bfe_u32 v36, v6, 16, 1
	v_bfe_u32 v37, v7, 16, 1
	v_bfe_u32 v38, v4, 16, 1
	v_bfe_u32 v39, v5, 16, 1
	v_add3_u32 v10, v10, v32, s91
	v_add3_u32 v11, v11, v33, s91
	v_add3_u32 v8, v8, v34, s91
	v_add3_u32 v9, v9, v35, s91
	v_add3_u32 v6, v6, v36, s91
	v_add3_u32 v7, v7, v37, s91
	v_add3_u32 v4, v4, v38, s91
	v_add3_u32 v5, v5, v39, s91
	v_lshl_add_u64 v[14:15], s[0:1], 0, v[130:131]
	s_mov_b32 s37, 0x7060302
	s_lshl_b32 s92, s53, 1
	s_cmp_lt_u32 s52, 2
	s_cbranch_scc0 .Lf3_caseB
	s_lshl_b32 s46, s50, 1
	v_perm_b32 v28, v4, v5, s37
	v_perm_b32 v29, v6, v7, s37
	v_perm_b32 v30, v8, v9, s37
	v_perm_b32 v31, v10, v11, s37
	s_branch .Lf3_st
.Lf3_caseB:
	s_lshl_b32 s46, s40, 1
	v_perm_b32 v28, v11, v10, s37
	v_perm_b32 v29, v9, v8, s37
	v_perm_b32 v30, v7, v6, s37
	v_perm_b32 v31, v5, v4, s37
.Lf3_st:
	s_mov_b32 s47, 0
	v_lshl_add_u64 v[16:17], v[14:15], 0, s[46:47]
	v_lshl_add_u64 v[12:13], v[16:17], 0, s[92:93]
	global_store_dwordx4 v[16:17], v[28:31], off
	global_store_dwordx4 v[12:13], v[28:31], off offset:62
	s_mov_b64 s[36:37], 0
	s_branch .LBB0_480
.Lf3_slow:
	v_lshl_add_u32 v12, s52, 8, v0
	s_movk_i32 s36, 0x200
	s_movk_i32 s46, 0x1ff
	v_cmp_gt_i32_e64 s[36:37], s36, v12
	v_cmp_lt_i32_e32 vcc, s46, v12
	s_mov_b64 s[46:47], 0
	s_and_saveexec_b64 s[48:49], vcc
	s_xor_b64 s[48:49], exec, s[48:49]
	s_and_b64 s[46:47], s[38:39], exec
	s_or_saveexec_b64 s[48:49], s[48:49]
	v_and_b32_e32 v12, 0x1ff, v12
	v_cvt_f32_u32_e32 v13, v12
	v_mov_b64_e32 v[16:17], s[40:41]
	v_fmamk_f32 v26, v13, 0x3cc4df2d, v250
	v_mul_f32_e32 v13, v18, v26
	v_mul_f32_e32 v13, 0x3fb8aa3b, v13
	v_exp_f32_e32 v13, v13
	s_nop 0
	v_mul_f32_e32 v10, v13, v10
	s_xor_b64 exec, exec, s[48:49]
	s_cbranch_execz .LBB0_489
	s_andn2_b64 vcc, exec, s[28:29]
	s_cbranch_vccnz .LBB0_488
	v_or_b32_e32 v13, s55, v12
	v_readlane_b32 s4, v252, 17
	v_lshlrev_b32_e32 v13, 2, v13
	v_readlane_b32 s10, v252, 23
	v_readlane_b32 s11, v252, 24
	v_readlane_b32 s5, v252, 18
	v_readlane_b32 s6, v252, 19
	v_readlane_b32 s7, v252, 20
	v_readlane_b32 s8, v252, 21
	v_readlane_b32 s9, v252, 22
	global_load_dword v13, v13, s[10:11]
	v_readlane_b32 s12, v252, 25
	v_readlane_b32 s13, v252, 26
	v_readlane_b32 s14, v252, 27
	v_readlane_b32 s15, v252, 28
	v_readlane_b32 s16, v252, 29
	v_readlane_b32 s17, v252, 30
	v_readlane_b32 s18, v252, 31
	v_readlane_b32 s19, v252, 32
	s_waitcnt vmcnt(0)
	v_add_f32_e32 v10, v10, v13
